# v47 plus attention fast-tail back-edge rotation (exit test and loop-carried moves parked before the stage barrier)
# baseline (speedup 1.0000x reference)
; #define LAS __attribute__((address_space(3)))
; __device__ __forceinline__ unsigned cvtpk2(float lo, float hi) { const f32x2 v = {lo, hi}; const bf16x2_n b = __builtin_convertvector(v, bf16x2_n); return __builtin_bit_cast(unsigned, b); }
; __device__ __forceinline__ void a2_exp_pack(f32x16& st0, f32x16& st1, float& lsum, bf16x8 (&pf)[4]) {
;     float ps = 0.f;
; #pragma unroll
;     for (int r = 0; r < 16; ++r) { st0[r] = __builtin_amdgcn_exp2f(st0[r]); st1[r] = __builtin_amdgcn_exp2f(st1[r]); ps += st0[r] + st1[r]; }
;     lsum += ps;
;     u32x4 w;
;     w.x = cvtpk2(st0[0], st0[1]); w.y = cvtpk2(st0[2], st0[3]); w.z = cvtpk2(st0[4], st0[5]); w.w = cvtpk2(st0[6], st0[7]); pf[0] = __builtin_bit_cast(bf16x8, w);
;     w.x = cvtpk2(st0[8], st0[9]); w.y = cvtpk2(st0[10], st0[11]); w.z = cvtpk2(st0[12], st0[13]); w.w = cvtpk2(st0[14], st0[15]); pf[1] = __builtin_bit_cast(bf16x8, w);
;     w.x = cvtpk2(st1[0], st1[1]); w.y = cvtpk2(st1[2], st1[3]); w.z = cvtpk2(st1[4], st1[5]); w.w = cvtpk2(st1[6], st1[7]); pf[2] = __builtin_bit_cast(bf16x8, w);
;     w.x = cvtpk2(st1[8], st1[9]); w.y = cvtpk2(st1[10], st1[11]); w.z = cvtpk2(st1[12], st1[13]); w.w = cvtpk2(st1[14], st1[15]); pf[3] = __builtin_bit_cast(bf16x8, w);
; }
; __device__ __forceinline__ void a2_pv(const LAS unsigned char* vb, const bf16x8 (&pf)[4], f32x16& ot0, f32x16& ot1) {
; #pragma unroll
;     for (int s = 0; s < 4; ++s) {
;         const s16x4 a00 = __builtin_bit_cast(s16x4, __builtin_amdgcn_ds_read_tr16_b64_v4i16((LAS s16x4*)(vb + (16 * s) * 64)));
;         const s16x4 a01 = __builtin_bit_cast(s16x4, __builtin_amdgcn_ds_read_tr16_b64_v4i16((LAS s16x4*)(vb + (16 * s + 8) * 64)));
;         const s16x4 a10 = __builtin_bit_cast(s16x4, __builtin_amdgcn_ds_read_tr16_b64_v4i16((LAS s16x4*)(vb + 8192 + (16 * s) * 64)));
;         const s16x4 a11 = __builtin_bit_cast(s16x4, __builtin_amdgcn_ds_read_tr16_b64_v4i16((LAS s16x4*)(vb + 8192 + (16 * s + 8) * 64)));
;         const bf16x8 va0 = (bf16x8){a00[0], a00[1], a00[2], a00[3], a01[0], a01[1], a01[2], a01[3]};
;         const bf16x8 va1 = (bf16x8){a10[0], a10[1], a10[2], a10[3], a11[0], a11[1], a11[2], a11[3]};
;         ot0 = __builtin_amdgcn_mfma_f32_32x32x16_bf16(va0, pf[s], ot0, 0, 0, 0); ot1 = __builtin_amdgcn_mfma_f32_32x32x16_bf16(va1, pf[s], ot1, 0, 0, 0); }
; }
.LBB0_832:
	v_add_u32_e32 v0, v2, v218
	v_exp_f32_e32 v199, v112
	v_exp_f32_e32 v7, v96
	v_exp_f32_e32 v113, v113
	v_exp_f32_e32 v9, v97
	v_exp_f32_e32 v201, v114
	v_exp_f32_e32 v3, v98
	v_exp_f32_e32 v115, v115
	v_exp_f32_e32 v5, v99
	v_exp_f32_e32 v203, v116
	v_exp_f32_e32 v15, v117
	v_exp_f32_e32 v13, v118
	v_exp_f32_e32 v11, v119
	s_waitcnt vmcnt(0)
	ds_read_b64_tr_b16 v[96:97], v0 offset:26624
	ds_read_b64_tr_b16 v[98:99], v0 offset:27136
	ds_read_b64_tr_b16 v[214:215], v0 offset:34816
	ds_read_b64_tr_b16 v[216:217], v0 offset:35328
	ds_read_b64_tr_b16 v[224:225], v0 offset:27648
	ds_read_b64_tr_b16 v[226:227], v0 offset:28160
	v_cvt_pk_bf16_f32 v210, v199, v113
	v_cvt_pk_bf16_f32 v211, v201, v115
	v_cvt_pk_bf16_f32 v212, v203, v15
	v_cvt_pk_bf16_f32 v213, v13, v11
	v_exp_f32_e32 v209, v120
	v_exp_f32_e32 v207, v121
	s_waitcnt lgkmcnt(4)
	v_mfma_f32_32x32x16_bf16 v[16:31], v[96:99], v[210:213], v[16:31]
	v_exp_f32_e32 v205, v122
	v_exp_f32_e32 v121, v123
	v_exp_f32_e32 v117, v124
	ds_read_b64_tr_b16 v[228:229], v0 offset:35840
	ds_read_b64_tr_b16 v[230:231], v0 offset:36352
	v_exp_f32_e32 v119, v125
	v_exp_f32_e32 v99, v126
	v_exp_f32_e32 v97, v127
	s_waitcnt lgkmcnt(4)
	v_mfma_f32_32x32x16_bf16 v[32:47], v[214:217], v[210:213], v[32:47]
	v_cvt_pk_bf16_f32 v232, v209, v207
	v_cvt_pk_bf16_f32 v233, v205, v121
	v_cvt_pk_bf16_f32 v234, v117, v119
	v_cvt_pk_bf16_f32 v235, v99, v97
	v_exp_f32_e32 v125, v100
	v_exp_f32_e32 v213, v101
	v_exp_f32_e32 v211, v102
	s_waitcnt lgkmcnt(2)
	v_mfma_f32_32x32x16_bf16 v[16:31], v[224:227], v[232:235], v[16:31]
	v_exp_f32_e32 v217, v103
	ds_read_b64_tr_b16 v[224:225], v0 offset:28672
	ds_read_b64_tr_b16 v[226:227], v0 offset:29184
	v_cvt_pk_bf16_f32 v100, v7, v9
	v_cvt_pk_bf16_f32 v101, v3, v5
	v_cvt_pk_bf16_f32 v102, v125, v213
	v_cvt_pk_bf16_f32 v103, v211, v217
	v_exp_f32_e32 v123, v104
	s_waitcnt lgkmcnt(2)
	v_mfma_f32_32x32x16_bf16 v[32:47], v[228:231], v[232:235], v[32:47]
	ds_read_b64_tr_b16 v[228:229], v0 offset:36864
	ds_read_b64_tr_b16 v[230:231], v0 offset:37376
	ds_read_b64_tr_b16 v[232:233], v0 offset:29696
	ds_read_b64_tr_b16 v[234:235], v0 offset:30208
	v_exp_f32_e32 v127, v105
	v_exp_f32_e32 v105, v106
	v_exp_f32_e32 v215, v107
	v_exp_f32_e32 v107, v108
	v_exp_f32_e32 v109, v109
	v_exp_f32_e32 v198, v64
	s_waitcnt lgkmcnt(4)
	v_mfma_f32_32x32x16_bf16 v[16:31], v[224:227], v[100:103], v[16:31]
	ds_read_b64_tr_b16 v[224:225], v0 offset:37888
	ds_read_b64_tr_b16 v[226:227], v0 offset:38400
	v_exp_f32_e32 v6, v80
	v_exp_f32_e32 v112, v65
	v_exp_f32_e32 v8, v81
	v_exp_f32_e32 v200, v66
	v_exp_f32_e32 v2, v82
	v_exp_f32_e32 v114, v67
	s_waitcnt lgkmcnt(4)
	v_mfma_f32_32x32x16_bf16 v[32:47], v[228:231], v[100:103], v[32:47]
	v_exp_f32_e32 v103, v110
	v_exp_f32_e32 v101, v111
	v_exp_f32_e32 v4, v83
	v_cvt_pk_bf16_f32 v228, v123, v127
	v_cvt_pk_bf16_f32 v229, v105, v215
	v_cvt_pk_bf16_f32 v230, v107, v109
	v_cvt_pk_bf16_f32 v231, v103, v101
	v_pk_add_f32 v[64:65], v[6:7], v[198:199]
	v_pk_add_f32 v[66:67], v[8:9], v[112:113]
	s_waitcnt lgkmcnt(2)
	v_mfma_f32_32x32x16_bf16 v[16:31], v[232:235], v[228:231], v[16:31]
	v_add_f32_e64 v64, v64, 0
	v_add_f32_e64 v65, v65, 0
	v_exp_f32_e32 v202, v68
	v_pk_add_f32 v[64:65], v[66:67], v[64:65]
	v_pk_add_f32 v[66:67], v[2:3], v[200:201]
	v_exp_f32_e32 v14, v69
	v_pk_add_f32 v[64:65], v[66:67], v[64:65]
	v_pk_add_f32 v[66:67], v[4:5], v[114:115]
	s_waitcnt lgkmcnt(0)
	v_mfma_f32_32x32x16_bf16 v[32:47], v[224:227], v[228:231], v[32:47]
	v_add_f32_e64 v110, v66, v64
	v_add_f32_e64 v111, v67, v65
	v_exp_f32_e32 v12, v70
	v_exp_f32_e32 v10, v71
	ds_read_b64_tr_b16 v[64:65], v0 offset:30720
	ds_read_b64_tr_b16 v[66:67], v0 offset:31232
	v_exp_f32_e32 v124, v84
	v_exp_f32_e32 v208, v72
	v_exp_f32_e32 v206, v73
	v_exp_f32_e32 v204, v74
	v_exp_f32_e32 v120, v75
	ds_read_b64_tr_b16 v[72:73], v0 offset:38912
	ds_read_b64_tr_b16 v[74:75], v0 offset:39424
	ds_read_b64_tr_b16 v[80:81], v0 offset:31744
	ds_read_b64_tr_b16 v[82:83], v0 offset:32256
	v_exp_f32_e32 v212, v85
	v_cvt_pk_bf16_f32 v68, v198, v112
	v_cvt_pk_bf16_f32 v69, v200, v114
	v_cvt_pk_bf16_f32 v70, v202, v14
	v_cvt_pk_bf16_f32 v71, v12, v10
	v_pk_add_f32 v[220:221], v[124:125], v[202:203]
	v_exp_f32_e32 v210, v86
	s_waitcnt lgkmcnt(4)
	v_mfma_f32_32x32x16_bf16 v[16:31], v[64:67], v[68:71], v[16:31]
	v_add_f32_e64 v64, v220, v110
	v_add_f32_e64 v65, v221, v111
	v_add_f32_e64 v14, v212, v14
	v_add_f32_e64 v15, v213, v15
	v_exp_f32_e32 v216, v87
	v_exp_f32_e32 v116, v76
	v_exp_f32_e32 v118, v77
	v_exp_f32_e32 v98, v78
	v_exp_f32_e32 v96, v79
	s_waitcnt lgkmcnt(2)
; #define LAS __attribute__((address_space(3)))
; __device__ __forceinline__ void a2_pv(const LAS unsigned char* vb, const bf16x8 (&pf)[4], f32x16& ot0, f32x16& ot1) {
; #pragma unroll
;     for (int s = 0; s < 4; ++s) {
;         const s16x4 a00 = __builtin_bit_cast(s16x4, __builtin_amdgcn_ds_read_tr16_b64_v4i16((LAS s16x4*)(vb + (16 * s) * 64)));
;         const s16x4 a01 = __builtin_bit_cast(s16x4, __builtin_amdgcn_ds_read_tr16_b64_v4i16((LAS s16x4*)(vb + (16 * s + 8) * 64)));
;         const s16x4 a10 = __builtin_bit_cast(s16x4, __builtin_amdgcn_ds_read_tr16_b64_v4i16((LAS s16x4*)(vb + 8192 + (16 * s) * 64)));
;         const s16x4 a11 = __builtin_bit_cast(s16x4, __builtin_amdgcn_ds_read_tr16_b64_v4i16((LAS s16x4*)(vb + 8192 + (16 * s + 8) * 64)));
;         const bf16x8 va0 = (bf16x8){a00[0], a00[1], a00[2], a00[3], a01[0], a01[1], a01[2], a01[3]};
;         const bf16x8 va1 = (bf16x8){a10[0], a10[1], a10[2], a10[3], a11[0], a11[1], a11[2], a11[3]};
;         ot0 = __builtin_amdgcn_mfma_f32_32x32x16_bf16(va0, pf[s], ot0, 0, 0, 0); ot1 = __builtin_amdgcn_mfma_f32_32x32x16_bf16(va1, pf[s], ot1, 0, 0, 0); }
; }
; __device__ __forceinline__ void attn2_unit(bf16_t* Z, const bf16_t* Hb, const float* rc, const float* rs, LAS unsigned char* lds, int b, int h, int qblk) {
;     ...
;             a2_exp_pack(sa0, sa1, lsum, pa);
;             a2_pv(vb, pa, ot0, ot1);
;             a2_exp_pack(sb0, sb1, lsum, pb);
;             a2_pv(vb + 64 * 64, pb, ot0, ot1);
;         } else if (2 * kp <= cw) {
;             f32x16 sa0, sa1; bf16x8 pa[4];
;             a2_qk(kb, qf, cneg, sa0, sa1);
;             const float mt = a2_max(sa0, sa1);
;             if (kp == 0 || __builtin_amdgcn_ballot_w64(mt > 8.f) != 0ull) {
;                 const float delta = (kp == 0) ? mt : fmaxf(mt, 0.f), alpha = (kp == 0) ? 0.f : __builtin_amdgcn_exp2f(-delta);
;                 mrun += delta; lsum *= alpha;
; #pragma unroll
;                 for (int r = 0; r < 16; ++r) { ot0[r] *= alpha; ot1[r] *= alpha; sa0[r] -= delta; sa1[r] -= delta; cneg[r] = -mrun; }
;             }
;             a2_exp_pack(sa0, sa1, lsum, pa);
;             a2_pv(vb, pa, ot0, ot1);
;         }
;         __syncthreads();
;     }
	v_mfma_f32_32x32x16_bf16 v[32:47], v[72:75], v[68:71], v[32:47]
	v_add_f32_e64 v14, v14, v64
	v_add_f32_e64 v15, v15, v65
	ds_read_b64_tr_b16 v[64:65], v0 offset:39936
	ds_read_b64_tr_b16 v[66:67], v0 offset:40448
	v_exp_f32_e32 v122, v88
	v_pk_add_f32 v[12:13], v[210:211], v[12:13]
	v_pk_add_f32 v[68:69], v[216:217], v[10:11]
	v_pk_add_f32 v[14:15], v[12:13], v[14:15]
	v_cvt_pk_bf16_f32 v10, v208, v206
	v_cvt_pk_bf16_f32 v11, v204, v120
	v_cvt_pk_bf16_f32 v12, v116, v118
	v_cvt_pk_bf16_f32 v13, v98, v96
	v_pk_add_f32 v[14:15], v[68:69], v[14:15]
	v_pk_add_f32 v[68:69], v[122:123], v[208:209]
	s_waitcnt lgkmcnt(2)
	v_mfma_f32_32x32x16_bf16 v[16:31], v[80:83], v[10:13], v[16:31]
	v_add_f32_e64 v14, v68, v14
	v_add_f32_e64 v15, v69, v15
	ds_read_b64_tr_b16 v[68:69], v0 offset:32768
	ds_read_b64_tr_b16 v[70:71], v0 offset:33280
	v_exp_f32_e32 v126, v89
	v_exp_f32_e32 v104, v90
	v_cvt_pk_bf16_f32 v7, v2, v4
	v_exp_f32_e32 v214, v91
	v_cvt_pk_bf16_f32 v6, v6, v8
	s_waitcnt lgkmcnt(2)
	v_mfma_f32_32x32x16_bf16 v[32:47], v[64:67], v[10:13], v[32:47]
	ds_read_b64_tr_b16 v[2:3], v0 offset:40960
	ds_read_b64_tr_b16 v[4:5], v0 offset:41472
	ds_read_b64_tr_b16 v[10:11], v0 offset:33792
	ds_read_b64_tr_b16 v[12:13], v0 offset:34304
	v_cvt_pk_bf16_f32 v8, v124, v212
	v_cvt_pk_bf16_f32 v9, v210, v216
	v_pk_add_f32 v[72:73], v[126:127], v[206:207]
	v_pk_add_f32 v[64:65], v[104:105], v[204:205]
	v_pk_add_f32 v[14:15], v[72:73], v[14:15]
	v_exp_f32_e32 v106, v92
	s_waitcnt lgkmcnt(4)
	v_mfma_f32_32x32x16_bf16 v[16:31], v[68:71], v[6:9], v[16:31]
	v_add_f32_e64 v14, v64, v14
	v_add_f32_e64 v15, v65, v15
	v_add_f32_e64 v64, v214, v120
	v_add_f32_e64 v65, v215, v121
	v_exp_f32_e32 v108, v93
	v_exp_f32_e32 v102, v94
	v_exp_f32_e32 v100, v95
	v_pk_add_f32 v[14:15], v[64:65], v[14:15]
	ds_read_b64_tr_b16 v[64:65], v0 offset:41984
	ds_read_b64_tr_b16 v[66:67], v0 offset:42496
	s_waitcnt lgkmcnt(4)
	v_mfma_f32_32x32x16_bf16 v[32:47], v[2:5], v[6:9], v[32:47]
	v_add_f32_e64 v2, v106, v116
	v_add_f32_e64 v3, v107, v117
	v_cvt_pk_bf16_f32 v4, v106, v108
	v_add_f32_e64 v6, v2, v14
	v_add_f32_e64 v7, v3, v15
	v_cvt_pk_bf16_f32 v2, v122, v126
	v_cvt_pk_bf16_f32 v3, v104, v214
	v_cvt_pk_bf16_f32 v5, v102, v100
	v_pk_add_f32 v[8:9], v[108:109], v[118:119]
	v_mov_b32_e32 v14, v55
	s_waitcnt lgkmcnt(2)
	v_mfma_f32_32x32x16_bf16 v[16:31], v[10:13], v[2:5], v[16:31]
	v_add_f32_e64 v6, v8, v6
	v_add_f32_e64 v7, v9, v7
	v_add_f32_e64 v8, v102, v98
	v_add_f32_e64 v9, v103, v99
	v_mov_b32_e32 v10, v59
	v_pk_add_f32 v[6:7], v[8:9], v[6:7]
	v_pk_add_f32 v[8:9], v[100:101], v[96:97]
	v_mov_b32_e32 v11, v58
	v_pk_add_f32 v[6:7], v[8:9], v[6:7]
	s_waitcnt lgkmcnt(0)
	v_mfma_f32_32x32x16_bf16 v[32:47], v[64:67], v[2:5], v[32:47]
	v_add_f32_e32 v0, v169, v7
	v_add_f32_e32 v0, v6, v0
	s_add_i32 s65, s65, 1
	s_add_i32 s69, s69, 2
	s_add_i32 s6, s43, s65
	v_lshl_add_u64 v[176:177], v[176:177], 0, v[174:175]
	v_lshl_add_u64 v[178:179], v[178:179], 0, s[20:21]
	v_lshl_add_u64 v[180:181], v[180:181], 0, s[20:21]
	v_lshl_add_u64 v[184:185], v[184:185], 0, v[182:183]
	v_lshl_add_u64 v[188:189], v[188:189], 0, v[186:187]
	s_cmp_lg_u32 s6, 1
	v_lshl_add_u64 v[196:197], v[196:197], 0, v[190:191]
	s_cbranch_scc0 .Lattn_exit_0
	v_mov_b32_e32 v169, v0
	s_bitcmp1_b32 s65, 0
	s_cselect_b32 s6, 0, 0xa800
	s_cmp_ge_u32 s65, s36
	s_waitcnt vmcnt(0) lgkmcnt(0)
	s_barrier
	s_cbranch_scc0 .LBB0_810
	s_branch .LBB0_813
.Lattn_exit_0:
	s_waitcnt vmcnt(0) lgkmcnt(0)
	s_barrier
	s_nop 7
	s_nop 7
	v_mov_b64_e32 v[110:111], v[30:31]
	v_mov_b32_e32 v6, v63
	v_mov_b32_e32 v7, v62
	v_mov_b32_e32 v8, v61
	v_mov_b32_e32 v9, v60
	v_mov_b64_e32 v[126:127], v[46:47]
	v_mov_b32_e32 v12, v57
	v_mov_b32_e32 v13, v56
	v_mov_b32_e32 v15, v54
	v_mov_b32_e32 v171, v53
	v_mov_b32_e32 v198, v52
	v_mov_b32_e32 v199, v51
	v_mov_b32_e32 v200, v50
	v_mov_b32_e32 v201, v49
	v_mov_b32_e32 v4, v48
	v_mov_b32_e32 v5, v165
	v_mov_b64_e32 v[108:109], v[28:29]
	v_mov_b64_e32 v[106:107], v[26:27]
	v_mov_b64_e32 v[104:105], v[24:25]
	v_mov_b64_e32 v[102:103], v[22:23]
	v_mov_b64_e32 v[100:101], v[20:21]
	v_mov_b64_e32 v[98:99], v[18:19]
	v_mov_b64_e32 v[96:97], v[16:17]
	v_mov_b64_e32 v[124:125], v[44:45]
	v_mov_b64_e32 v[122:123], v[42:43]
	v_mov_b64_e32 v[120:121], v[40:41]
	v_mov_b64_e32 v[118:119], v[38:39]
	v_mov_b64_e32 v[116:117], v[36:37]
	v_mov_b64_e32 v[114:115], v[34:35]
	v_mov_b64_e32 v[112:113], v[32:33]
	s_branch .LBB0_837

; #define LAS __attribute__((address_space(3)))
; __device__ __forceinline__ unsigned cvtpk2(float lo, float hi) { const f32x2 v = {lo, hi}; const bf16x2_n b = __builtin_convertvector(v, bf16x2_n); return __builtin_bit_cast(unsigned, b); }
; __device__ __forceinline__ void a2_exp_pack(f32x16& st0, f32x16& st1, float& lsum, bf16x8 (&pf)[4]) {
;     float ps = 0.f;
; #pragma unroll
;     for (int r = 0; r < 16; ++r) { st0[r] = __builtin_amdgcn_exp2f(st0[r]); st1[r] = __builtin_amdgcn_exp2f(st1[r]); ps += st0[r] + st1[r]; }
;     lsum += ps;
;     u32x4 w;
;     w.x = cvtpk2(st0[0], st0[1]); w.y = cvtpk2(st0[2], st0[3]); w.z = cvtpk2(st0[4], st0[5]); w.w = cvtpk2(st0[6], st0[7]); pf[0] = __builtin_bit_cast(bf16x8, w);
;     w.x = cvtpk2(st0[8], st0[9]); w.y = cvtpk2(st0[10], st0[11]); w.z = cvtpk2(st0[12], st0[13]); w.w = cvtpk2(st0[14], st0[15]); pf[1] = __builtin_bit_cast(bf16x8, w);
;     w.x = cvtpk2(st1[0], st1[1]); w.y = cvtpk2(st1[2], st1[3]); w.z = cvtpk2(st1[4], st1[5]); w.w = cvtpk2(st1[6], st1[7]); pf[2] = __builtin_bit_cast(bf16x8, w);
;     w.x = cvtpk2(st1[8], st1[9]); w.y = cvtpk2(st1[10], st1[11]); w.z = cvtpk2(st1[12], st1[13]); w.w = cvtpk2(st1[14], st1[15]); pf[3] = __builtin_bit_cast(bf16x8, w);
; }
; __device__ __forceinline__ void a2_pv(const LAS unsigned char* vb, const bf16x8 (&pf)[4], f32x16& ot0, f32x16& ot1) {
; #pragma unroll
;     for (int s = 0; s < 4; ++s) {
;         const s16x4 a00 = __builtin_bit_cast(s16x4, __builtin_amdgcn_ds_read_tr16_b64_v4i16((LAS s16x4*)(vb + (16 * s) * 64)));
;         const s16x4 a01 = __builtin_bit_cast(s16x4, __builtin_amdgcn_ds_read_tr16_b64_v4i16((LAS s16x4*)(vb + (16 * s + 8) * 64)));
;         const s16x4 a10 = __builtin_bit_cast(s16x4, __builtin_amdgcn_ds_read_tr16_b64_v4i16((LAS s16x4*)(vb + 8192 + (16 * s) * 64)));
;         const s16x4 a11 = __builtin_bit_cast(s16x4, __builtin_amdgcn_ds_read_tr16_b64_v4i16((LAS s16x4*)(vb + 8192 + (16 * s + 8) * 64)));
;         const bf16x8 va0 = (bf16x8){a00[0], a00[1], a00[2], a00[3], a01[0], a01[1], a01[2], a01[3]};
;         const bf16x8 va1 = (bf16x8){a10[0], a10[1], a10[2], a10[3], a11[0], a11[1], a11[2], a11[3]};
;         ot0 = __builtin_amdgcn_mfma_f32_32x32x16_bf16(va0, pf[s], ot0, 0, 0, 0); ot1 = __builtin_amdgcn_mfma_f32_32x32x16_bf16(va1, pf[s], ot1, 0, 0, 0); }
; }
.LBB0_878:
	v_add_u32_e32 v0, v2, v218
	v_exp_f32_e32 v197, v112
	v_exp_f32_e32 v7, v96
	v_exp_f32_e32 v113, v113
	v_exp_f32_e32 v9, v97
	v_exp_f32_e32 v199, v114
	v_exp_f32_e32 v3, v98
	v_exp_f32_e32 v115, v115
	v_exp_f32_e32 v5, v99
	v_exp_f32_e32 v201, v116
	v_exp_f32_e32 v15, v117
	v_exp_f32_e32 v13, v118
	v_exp_f32_e32 v11, v119
	s_waitcnt vmcnt(0)
	ds_read_b64_tr_b16 v[96:97], v0 offset:26624
	ds_read_b64_tr_b16 v[98:99], v0 offset:27136
	ds_read_b64_tr_b16 v[212:213], v0 offset:34816
	ds_read_b64_tr_b16 v[214:215], v0 offset:35328
	ds_read_b64_tr_b16 v[224:225], v0 offset:27648
	ds_read_b64_tr_b16 v[226:227], v0 offset:28160
	v_cvt_pk_bf16_f32 v208, v197, v113
	v_cvt_pk_bf16_f32 v209, v199, v115
	v_cvt_pk_bf16_f32 v210, v201, v15
	v_cvt_pk_bf16_f32 v211, v13, v11
	v_exp_f32_e32 v207, v120
	v_exp_f32_e32 v205, v121
	s_waitcnt lgkmcnt(4)
	v_mfma_f32_32x32x16_bf16 v[16:31], v[96:99], v[208:211], v[16:31]
	v_exp_f32_e32 v203, v122
	v_exp_f32_e32 v121, v123
	v_exp_f32_e32 v117, v124
	ds_read_b64_tr_b16 v[228:229], v0 offset:35840
	ds_read_b64_tr_b16 v[230:231], v0 offset:36352
	v_exp_f32_e32 v119, v125
	v_exp_f32_e32 v99, v126
	v_exp_f32_e32 v97, v127
	s_waitcnt lgkmcnt(4)
	v_mfma_f32_32x32x16_bf16 v[32:47], v[212:215], v[208:211], v[32:47]
	v_cvt_pk_bf16_f32 v232, v207, v205
	v_cvt_pk_bf16_f32 v233, v203, v121
	v_cvt_pk_bf16_f32 v234, v117, v119
	v_cvt_pk_bf16_f32 v235, v99, v97
	v_exp_f32_e32 v125, v100
	v_exp_f32_e32 v211, v101
	v_exp_f32_e32 v209, v102
	s_waitcnt lgkmcnt(2)
	v_mfma_f32_32x32x16_bf16 v[16:31], v[224:227], v[232:235], v[16:31]
	v_exp_f32_e32 v215, v103
	ds_read_b64_tr_b16 v[224:225], v0 offset:28672
	ds_read_b64_tr_b16 v[226:227], v0 offset:29184
	v_cvt_pk_bf16_f32 v100, v7, v9
	v_cvt_pk_bf16_f32 v101, v3, v5
	v_cvt_pk_bf16_f32 v102, v125, v211
	v_cvt_pk_bf16_f32 v103, v209, v215
	v_exp_f32_e32 v123, v104
	s_waitcnt lgkmcnt(2)
	v_mfma_f32_32x32x16_bf16 v[32:47], v[228:231], v[232:235], v[32:47]
	ds_read_b64_tr_b16 v[228:229], v0 offset:36864
	ds_read_b64_tr_b16 v[230:231], v0 offset:37376
	ds_read_b64_tr_b16 v[232:233], v0 offset:29696
	ds_read_b64_tr_b16 v[234:235], v0 offset:30208
	v_exp_f32_e32 v127, v105
	v_exp_f32_e32 v105, v106
	v_exp_f32_e32 v213, v107
	v_exp_f32_e32 v107, v108
	v_exp_f32_e32 v109, v109
	v_exp_f32_e32 v196, v64
	s_waitcnt lgkmcnt(4)
	v_mfma_f32_32x32x16_bf16 v[16:31], v[224:227], v[100:103], v[16:31]
	ds_read_b64_tr_b16 v[224:225], v0 offset:37888
	ds_read_b64_tr_b16 v[226:227], v0 offset:38400
	v_exp_f32_e32 v6, v80
	v_exp_f32_e32 v112, v65
	v_exp_f32_e32 v8, v81
	v_exp_f32_e32 v198, v66
	v_exp_f32_e32 v2, v82
	v_exp_f32_e32 v114, v67
	s_waitcnt lgkmcnt(4)
	v_mfma_f32_32x32x16_bf16 v[32:47], v[228:231], v[100:103], v[32:47]
	v_exp_f32_e32 v103, v110
	v_exp_f32_e32 v101, v111
	v_exp_f32_e32 v4, v83
	v_cvt_pk_bf16_f32 v228, v123, v127
	v_cvt_pk_bf16_f32 v229, v105, v213
	v_cvt_pk_bf16_f32 v230, v107, v109
	v_cvt_pk_bf16_f32 v231, v103, v101
	v_pk_add_f32 v[64:65], v[6:7], v[196:197]
	v_pk_add_f32 v[66:67], v[8:9], v[112:113]
	s_waitcnt lgkmcnt(2)
	v_mfma_f32_32x32x16_bf16 v[16:31], v[232:235], v[228:231], v[16:31]
	v_add_f32_e64 v64, v64, 0
	v_add_f32_e64 v65, v65, 0
	v_exp_f32_e32 v200, v68
	v_pk_add_f32 v[64:65], v[66:67], v[64:65]
	v_pk_add_f32 v[66:67], v[2:3], v[198:199]
	v_exp_f32_e32 v14, v69
	v_pk_add_f32 v[64:65], v[66:67], v[64:65]
	v_pk_add_f32 v[66:67], v[4:5], v[114:115]
	s_waitcnt lgkmcnt(0)
	v_mfma_f32_32x32x16_bf16 v[32:47], v[224:227], v[228:231], v[32:47]
	v_add_f32_e64 v110, v66, v64
	v_add_f32_e64 v111, v67, v65
	v_exp_f32_e32 v12, v70
	v_exp_f32_e32 v10, v71
	ds_read_b64_tr_b16 v[64:65], v0 offset:30720
	ds_read_b64_tr_b16 v[66:67], v0 offset:31232
	v_exp_f32_e32 v124, v84
	v_exp_f32_e32 v206, v72
	v_exp_f32_e32 v204, v73
	v_exp_f32_e32 v202, v74
	v_exp_f32_e32 v120, v75
	ds_read_b64_tr_b16 v[72:73], v0 offset:38912
	ds_read_b64_tr_b16 v[74:75], v0 offset:39424
	ds_read_b64_tr_b16 v[80:81], v0 offset:31744
	ds_read_b64_tr_b16 v[82:83], v0 offset:32256
	v_exp_f32_e32 v210, v85
	v_cvt_pk_bf16_f32 v68, v196, v112
	v_cvt_pk_bf16_f32 v69, v198, v114
	v_cvt_pk_bf16_f32 v70, v200, v14
	v_cvt_pk_bf16_f32 v71, v12, v10
	v_pk_add_f32 v[216:217], v[124:125], v[200:201]
	v_exp_f32_e32 v208, v86
	s_waitcnt lgkmcnt(4)
	v_mfma_f32_32x32x16_bf16 v[16:31], v[64:67], v[68:71], v[16:31]
	v_add_f32_e64 v64, v216, v110
	v_add_f32_e64 v65, v217, v111
	v_add_f32_e64 v14, v210, v14
	v_add_f32_e64 v15, v211, v15
	v_exp_f32_e32 v214, v87
	v_exp_f32_e32 v116, v76
	v_exp_f32_e32 v118, v77
	v_exp_f32_e32 v98, v78
	v_exp_f32_e32 v96, v79
	s_waitcnt lgkmcnt(2)
; #define LAS __attribute__((address_space(3)))
; __device__ __forceinline__ void a2_pv(const LAS unsigned char* vb, const bf16x8 (&pf)[4], f32x16& ot0, f32x16& ot1) {
; #pragma unroll
;     for (int s = 0; s < 4; ++s) {
;         const s16x4 a00 = __builtin_bit_cast(s16x4, __builtin_amdgcn_ds_read_tr16_b64_v4i16((LAS s16x4*)(vb + (16 * s) * 64)));
;         const s16x4 a01 = __builtin_bit_cast(s16x4, __builtin_amdgcn_ds_read_tr16_b64_v4i16((LAS s16x4*)(vb + (16 * s + 8) * 64)));
;         const s16x4 a10 = __builtin_bit_cast(s16x4, __builtin_amdgcn_ds_read_tr16_b64_v4i16((LAS s16x4*)(vb + 8192 + (16 * s) * 64)));
;         const s16x4 a11 = __builtin_bit_cast(s16x4, __builtin_amdgcn_ds_read_tr16_b64_v4i16((LAS s16x4*)(vb + 8192 + (16 * s + 8) * 64)));
;         const bf16x8 va0 = (bf16x8){a00[0], a00[1], a00[2], a00[3], a01[0], a01[1], a01[2], a01[3]};
;         const bf16x8 va1 = (bf16x8){a10[0], a10[1], a10[2], a10[3], a11[0], a11[1], a11[2], a11[3]};
;         ot0 = __builtin_amdgcn_mfma_f32_32x32x16_bf16(va0, pf[s], ot0, 0, 0, 0); ot1 = __builtin_amdgcn_mfma_f32_32x32x16_bf16(va1, pf[s], ot1, 0, 0, 0); }
; }
; __device__ __forceinline__ void attn2_unit(bf16_t* Z, const bf16_t* Hb, const float* rc, const float* rs, LAS unsigned char* lds, int b, int h, int qblk) {
;     ...
;             a2_exp_pack(sa0, sa1, lsum, pa);
;             a2_pv(vb, pa, ot0, ot1);
;             a2_exp_pack(sb0, sb1, lsum, pb);
;             a2_pv(vb + 64 * 64, pb, ot0, ot1);
;         } else if (2 * kp <= cw) {
;             f32x16 sa0, sa1; bf16x8 pa[4];
;             a2_qk(kb, qf, cneg, sa0, sa1);
;             const float mt = a2_max(sa0, sa1);
;             if (kp == 0 || __builtin_amdgcn_ballot_w64(mt > 8.f) != 0ull) {
;                 const float delta = (kp == 0) ? mt : fmaxf(mt, 0.f), alpha = (kp == 0) ? 0.f : __builtin_amdgcn_exp2f(-delta);
;                 mrun += delta; lsum *= alpha;
; #pragma unroll
;                 for (int r = 0; r < 16; ++r) { ot0[r] *= alpha; ot1[r] *= alpha; sa0[r] -= delta; sa1[r] -= delta; cneg[r] = -mrun; }
;             }
;             a2_exp_pack(sa0, sa1, lsum, pa);
;             a2_pv(vb, pa, ot0, ot1);
;         }
;         __syncthreads();
;     }
	v_mfma_f32_32x32x16_bf16 v[32:47], v[72:75], v[68:71], v[32:47]
	v_add_f32_e64 v14, v14, v64
	v_add_f32_e64 v15, v15, v65
	ds_read_b64_tr_b16 v[64:65], v0 offset:39936
	ds_read_b64_tr_b16 v[66:67], v0 offset:40448
	v_exp_f32_e32 v122, v88
	v_pk_add_f32 v[12:13], v[208:209], v[12:13]
	v_pk_add_f32 v[68:69], v[214:215], v[10:11]
	v_pk_add_f32 v[14:15], v[12:13], v[14:15]
	v_cvt_pk_bf16_f32 v10, v206, v204
	v_cvt_pk_bf16_f32 v11, v202, v120
	v_cvt_pk_bf16_f32 v12, v116, v118
	v_cvt_pk_bf16_f32 v13, v98, v96
	v_pk_add_f32 v[14:15], v[68:69], v[14:15]
	v_pk_add_f32 v[68:69], v[122:123], v[206:207]
	s_waitcnt lgkmcnt(2)
	v_mfma_f32_32x32x16_bf16 v[16:31], v[80:83], v[10:13], v[16:31]
	v_add_f32_e64 v14, v68, v14
	v_add_f32_e64 v15, v69, v15
	ds_read_b64_tr_b16 v[68:69], v0 offset:32768
	ds_read_b64_tr_b16 v[70:71], v0 offset:33280
	v_exp_f32_e32 v126, v89
	v_exp_f32_e32 v104, v90
	v_cvt_pk_bf16_f32 v7, v2, v4
	v_exp_f32_e32 v212, v91
	v_cvt_pk_bf16_f32 v6, v6, v8
	s_waitcnt lgkmcnt(2)
	v_mfma_f32_32x32x16_bf16 v[32:47], v[64:67], v[10:13], v[32:47]
	ds_read_b64_tr_b16 v[2:3], v0 offset:40960
	ds_read_b64_tr_b16 v[4:5], v0 offset:41472
	ds_read_b64_tr_b16 v[10:11], v0 offset:33792
	ds_read_b64_tr_b16 v[12:13], v0 offset:34304
	v_cvt_pk_bf16_f32 v8, v124, v210
	v_cvt_pk_bf16_f32 v9, v208, v214
	v_pk_add_f32 v[72:73], v[126:127], v[204:205]
	v_pk_add_f32 v[64:65], v[104:105], v[202:203]
	v_pk_add_f32 v[14:15], v[72:73], v[14:15]
	v_exp_f32_e32 v106, v92
	s_waitcnt lgkmcnt(4)
	v_mfma_f32_32x32x16_bf16 v[16:31], v[68:71], v[6:9], v[16:31]
	v_add_f32_e64 v14, v64, v14
	v_add_f32_e64 v15, v65, v15
	v_add_f32_e64 v64, v212, v120
	v_add_f32_e64 v65, v213, v121
	v_exp_f32_e32 v108, v93
	v_exp_f32_e32 v102, v94
	v_exp_f32_e32 v100, v95
	v_pk_add_f32 v[14:15], v[64:65], v[14:15]
	ds_read_b64_tr_b16 v[64:65], v0 offset:41984
	ds_read_b64_tr_b16 v[66:67], v0 offset:42496
	s_waitcnt lgkmcnt(4)
	v_mfma_f32_32x32x16_bf16 v[32:47], v[2:5], v[6:9], v[32:47]
	v_add_f32_e64 v2, v106, v116
	v_add_f32_e64 v3, v107, v117
	v_cvt_pk_bf16_f32 v4, v106, v108
	v_add_f32_e64 v6, v2, v14
	v_add_f32_e64 v7, v3, v15
	v_cvt_pk_bf16_f32 v2, v122, v126
	v_cvt_pk_bf16_f32 v3, v104, v212
	v_cvt_pk_bf16_f32 v5, v102, v100
	v_pk_add_f32 v[8:9], v[108:109], v[118:119]
	v_mov_b32_e32 v14, v55
	s_waitcnt lgkmcnt(2)
	v_mfma_f32_32x32x16_bf16 v[16:31], v[10:13], v[2:5], v[16:31]
	v_add_f32_e64 v6, v8, v6
	v_add_f32_e64 v7, v9, v7
	v_add_f32_e64 v8, v102, v98
	v_add_f32_e64 v9, v103, v99
	v_mov_b32_e32 v10, v59
	v_pk_add_f32 v[6:7], v[8:9], v[6:7]
	v_pk_add_f32 v[8:9], v[100:101], v[96:97]
	v_mov_b32_e32 v11, v58
	v_pk_add_f32 v[6:7], v[8:9], v[6:7]
	s_waitcnt lgkmcnt(0)
	v_mfma_f32_32x32x16_bf16 v[32:47], v[64:67], v[2:5], v[32:47]
	v_add_f32_e32 v0, v169, v7
	v_add_f32_e32 v0, v6, v0
	s_add_i32 s35, s35, 1
	s_add_i32 s56, s56, 2
	s_add_i32 s6, s46, s35
	v_lshl_add_u64 v[174:175], v[174:175], 0, v[170:171]
	v_lshl_add_u64 v[176:177], v[176:177], 0, s[20:21]
	v_lshl_add_u64 v[178:179], v[178:179], 0, s[20:21]
	v_lshl_add_u64 v[182:183], v[182:183], 0, v[180:181]
	v_lshl_add_u64 v[186:187], v[186:187], 0, v[184:185]
	s_cmp_lg_u32 s6, 1
	v_lshl_add_u64 v[190:191], v[190:191], 0, v[188:189]
	s_cbranch_scc0 .Lattn_exit_1
	v_mov_b32_e32 v169, v0
	s_bitcmp1_b32 s35, 0
	s_cselect_b32 s6, 0, 0xa800
	s_cmp_ge_u32 s35, s42
	s_waitcnt vmcnt(0) lgkmcnt(0)
	s_barrier
	s_cbranch_scc0 .LBB0_856
	s_branch .LBB0_859
.Lattn_exit_1:
	s_waitcnt vmcnt(0) lgkmcnt(0)
	s_barrier
	s_nop 7
	s_nop 7
	v_mov_b64_e32 v[110:111], v[30:31]
	v_mov_b32_e32 v6, v63
	v_mov_b32_e32 v7, v62
	v_mov_b32_e32 v8, v61
	v_mov_b32_e32 v9, v60
	v_mov_b64_e32 v[126:127], v[46:47]
	v_mov_b32_e32 v12, v57
	v_mov_b32_e32 v13, v56
	v_mov_b32_e32 v15, v54
	v_mov_b32_e32 v196, v53
	v_mov_b32_e32 v197, v52
	v_mov_b32_e32 v198, v51
	v_mov_b32_e32 v199, v50
	v_mov_b32_e32 v200, v49
	v_mov_b32_e32 v4, v48
	v_mov_b32_e32 v5, v165
	v_mov_b64_e32 v[108:109], v[28:29]
	v_mov_b64_e32 v[106:107], v[26:27]
	v_mov_b64_e32 v[104:105], v[24:25]
	v_mov_b64_e32 v[102:103], v[22:23]
	v_mov_b64_e32 v[100:101], v[20:21]
	v_mov_b64_e32 v[98:99], v[18:19]
	v_mov_b64_e32 v[96:97], v[16:17]
	v_mov_b64_e32 v[124:125], v[44:45]
	v_mov_b64_e32 v[122:123], v[42:43]
	v_mov_b64_e32 v[120:121], v[40:41]
	v_mov_b64_e32 v[118:119], v[38:39]
	v_mov_b64_e32 v[116:117], v[36:37]
	v_mov_b64_e32 v[114:115], v[34:35]
	v_mov_b64_e32 v[112:113], v[32:33]
	s_branch .LBB0_790

; #define LAS __attribute__((address_space(3)))
; __device__ __forceinline__ unsigned cvtpk2(float lo, float hi) { const f32x2 v = {lo, hi}; const bf16x2_n b = __builtin_convertvector(v, bf16x2_n); return __builtin_bit_cast(unsigned, b); }
; __device__ __forceinline__ void a2_exp_pack(f32x16& st0, f32x16& st1, float& lsum, bf16x8 (&pf)[4]) {
;     float ps = 0.f;
; #pragma unroll
;     for (int r = 0; r < 16; ++r) { st0[r] = __builtin_amdgcn_exp2f(st0[r]); st1[r] = __builtin_amdgcn_exp2f(st1[r]); ps += st0[r] + st1[r]; }
;     lsum += ps;
;     u32x4 w;
;     w.x = cvtpk2(st0[0], st0[1]); w.y = cvtpk2(st0[2], st0[3]); w.z = cvtpk2(st0[4], st0[5]); w.w = cvtpk2(st0[6], st0[7]); pf[0] = __builtin_bit_cast(bf16x8, w);
;     w.x = cvtpk2(st0[8], st0[9]); w.y = cvtpk2(st0[10], st0[11]); w.z = cvtpk2(st0[12], st0[13]); w.w = cvtpk2(st0[14], st0[15]); pf[1] = __builtin_bit_cast(bf16x8, w);
;     w.x = cvtpk2(st1[0], st1[1]); w.y = cvtpk2(st1[2], st1[3]); w.z = cvtpk2(st1[4], st1[5]); w.w = cvtpk2(st1[6], st1[7]); pf[2] = __builtin_bit_cast(bf16x8, w);
;     w.x = cvtpk2(st1[8], st1[9]); w.y = cvtpk2(st1[10], st1[11]); w.z = cvtpk2(st1[12], st1[13]); w.w = cvtpk2(st1[14], st1[15]); pf[3] = __builtin_bit_cast(bf16x8, w);
; }
; __device__ __forceinline__ void a2_pv(const LAS unsigned char* vb, const bf16x8 (&pf)[4], f32x16& ot0, f32x16& ot1) {
; #pragma unroll
;     for (int s = 0; s < 4; ++s) {
;         const s16x4 a00 = __builtin_bit_cast(s16x4, __builtin_amdgcn_ds_read_tr16_b64_v4i16((LAS s16x4*)(vb + (16 * s) * 64)));
;         const s16x4 a01 = __builtin_bit_cast(s16x4, __builtin_amdgcn_ds_read_tr16_b64_v4i16((LAS s16x4*)(vb + (16 * s + 8) * 64)));
;         const s16x4 a10 = __builtin_bit_cast(s16x4, __builtin_amdgcn_ds_read_tr16_b64_v4i16((LAS s16x4*)(vb + 8192 + (16 * s) * 64)));
;         const s16x4 a11 = __builtin_bit_cast(s16x4, __builtin_amdgcn_ds_read_tr16_b64_v4i16((LAS s16x4*)(vb + 8192 + (16 * s + 8) * 64)));
;         const bf16x8 va0 = (bf16x8){a00[0], a00[1], a00[2], a00[3], a01[0], a01[1], a01[2], a01[3]};
;         const bf16x8 va1 = (bf16x8){a10[0], a10[1], a10[2], a10[3], a11[0], a11[1], a11[2], a11[3]};
;         ot0 = __builtin_amdgcn_mfma_f32_32x32x16_bf16(va0, pf[s], ot0, 0, 0, 0); ot1 = __builtin_amdgcn_mfma_f32_32x32x16_bf16(va1, pf[s], ot1, 0, 0, 0); }
; }
.LBB0_2243:
	v_add_u32_e32 v0, v2, v218
	v_exp_f32_e32 v199, v112
	v_exp_f32_e32 v7, v96
	v_exp_f32_e32 v113, v113
	v_exp_f32_e32 v9, v97
	v_exp_f32_e32 v201, v114
	v_exp_f32_e32 v3, v98
	v_exp_f32_e32 v115, v115
	v_exp_f32_e32 v5, v99
	v_exp_f32_e32 v203, v116
	v_exp_f32_e32 v15, v117
	v_exp_f32_e32 v13, v118
	v_exp_f32_e32 v11, v119
	s_waitcnt vmcnt(0)
	ds_read_b64_tr_b16 v[96:97], v0 offset:26624
	ds_read_b64_tr_b16 v[98:99], v0 offset:27136
	ds_read_b64_tr_b16 v[214:215], v0 offset:34816
	ds_read_b64_tr_b16 v[216:217], v0 offset:35328
	ds_read_b64_tr_b16 v[220:221], v0 offset:27648
	ds_read_b64_tr_b16 v[222:223], v0 offset:28160
	v_cvt_pk_bf16_f32 v210, v199, v113
	v_cvt_pk_bf16_f32 v211, v201, v115
	v_cvt_pk_bf16_f32 v212, v203, v15
	v_cvt_pk_bf16_f32 v213, v13, v11
	v_exp_f32_e32 v209, v120
	v_exp_f32_e32 v207, v121
	s_waitcnt lgkmcnt(4)
	v_mfma_f32_32x32x16_bf16 v[16:31], v[96:99], v[210:213], v[16:31]
	v_exp_f32_e32 v205, v122
	v_exp_f32_e32 v121, v123
	v_exp_f32_e32 v117, v124
	ds_read_b64_tr_b16 v[224:225], v0 offset:35840
	ds_read_b64_tr_b16 v[226:227], v0 offset:36352
	v_exp_f32_e32 v119, v125
	v_exp_f32_e32 v99, v126
	v_exp_f32_e32 v97, v127
	s_waitcnt lgkmcnt(4)
	v_mfma_f32_32x32x16_bf16 v[32:47], v[214:217], v[210:213], v[32:47]
	v_cvt_pk_bf16_f32 v228, v209, v207
	v_cvt_pk_bf16_f32 v229, v205, v121
	v_cvt_pk_bf16_f32 v230, v117, v119
	v_cvt_pk_bf16_f32 v231, v99, v97
	v_exp_f32_e32 v125, v100
	v_exp_f32_e32 v213, v101
	v_exp_f32_e32 v211, v102
	s_waitcnt lgkmcnt(2)
	v_mfma_f32_32x32x16_bf16 v[16:31], v[220:223], v[228:231], v[16:31]
	v_exp_f32_e32 v217, v103
	ds_read_b64_tr_b16 v[220:221], v0 offset:28672
	ds_read_b64_tr_b16 v[222:223], v0 offset:29184
	v_cvt_pk_bf16_f32 v100, v7, v9
	v_cvt_pk_bf16_f32 v101, v3, v5
	v_cvt_pk_bf16_f32 v102, v125, v213
	v_cvt_pk_bf16_f32 v103, v211, v217
	v_exp_f32_e32 v123, v104
	s_waitcnt lgkmcnt(2)
	v_mfma_f32_32x32x16_bf16 v[32:47], v[224:227], v[228:231], v[32:47]
	ds_read_b64_tr_b16 v[224:225], v0 offset:36864
	ds_read_b64_tr_b16 v[226:227], v0 offset:37376
	ds_read_b64_tr_b16 v[228:229], v0 offset:29696
	ds_read_b64_tr_b16 v[230:231], v0 offset:30208
	v_exp_f32_e32 v127, v105
	v_exp_f32_e32 v105, v106
	v_exp_f32_e32 v215, v107
	v_exp_f32_e32 v107, v108
	v_exp_f32_e32 v109, v109
	v_exp_f32_e32 v198, v64
	s_waitcnt lgkmcnt(4)
	v_mfma_f32_32x32x16_bf16 v[16:31], v[220:223], v[100:103], v[16:31]
	ds_read_b64_tr_b16 v[220:221], v0 offset:37888
	ds_read_b64_tr_b16 v[222:223], v0 offset:38400
	v_exp_f32_e32 v6, v80
	v_exp_f32_e32 v112, v65
	v_exp_f32_e32 v8, v81
	v_exp_f32_e32 v200, v66
	v_exp_f32_e32 v2, v82
	v_exp_f32_e32 v114, v67
	s_waitcnt lgkmcnt(4)
	v_mfma_f32_32x32x16_bf16 v[32:47], v[224:227], v[100:103], v[32:47]
	v_exp_f32_e32 v103, v110
	v_exp_f32_e32 v101, v111
	v_exp_f32_e32 v4, v83
	v_cvt_pk_bf16_f32 v224, v123, v127
	v_cvt_pk_bf16_f32 v225, v105, v215
	v_cvt_pk_bf16_f32 v226, v107, v109
	v_cvt_pk_bf16_f32 v227, v103, v101
	v_pk_add_f32 v[64:65], v[6:7], v[198:199]
	v_pk_add_f32 v[66:67], v[8:9], v[112:113]
	s_waitcnt lgkmcnt(2)
	v_mfma_f32_32x32x16_bf16 v[16:31], v[228:231], v[224:227], v[16:31]
	v_add_f32_e64 v64, v64, 0
	v_add_f32_e64 v65, v65, 0
	v_exp_f32_e32 v202, v68
	v_pk_add_f32 v[64:65], v[66:67], v[64:65]
	v_pk_add_f32 v[66:67], v[2:3], v[200:201]
	v_exp_f32_e32 v14, v69
	v_pk_add_f32 v[64:65], v[66:67], v[64:65]
	v_pk_add_f32 v[66:67], v[4:5], v[114:115]
	s_waitcnt lgkmcnt(0)
	v_mfma_f32_32x32x16_bf16 v[32:47], v[220:223], v[224:227], v[32:47]
	v_add_f32_e64 v110, v66, v64
	v_add_f32_e64 v111, v67, v65
	v_exp_f32_e32 v12, v70
	v_exp_f32_e32 v10, v71
	ds_read_b64_tr_b16 v[64:65], v0 offset:30720
	ds_read_b64_tr_b16 v[66:67], v0 offset:31232
	v_exp_f32_e32 v124, v84
	v_exp_f32_e32 v208, v72
	v_exp_f32_e32 v206, v73
	v_exp_f32_e32 v204, v74
	v_exp_f32_e32 v120, v75
	ds_read_b64_tr_b16 v[72:73], v0 offset:38912
	ds_read_b64_tr_b16 v[74:75], v0 offset:39424
	ds_read_b64_tr_b16 v[80:81], v0 offset:31744
	ds_read_b64_tr_b16 v[82:83], v0 offset:32256
	v_exp_f32_e32 v212, v85
	v_cvt_pk_bf16_f32 v68, v198, v112
	v_cvt_pk_bf16_f32 v69, v200, v114
	v_cvt_pk_bf16_f32 v70, v202, v14
	v_cvt_pk_bf16_f32 v71, v12, v10
	v_pk_add_f32 v[220:221], v[124:125], v[202:203]
	v_exp_f32_e32 v210, v86
	s_waitcnt lgkmcnt(4)
; #define LAS __attribute__((address_space(3)))
; __device__ __forceinline__ void a2_pv(const LAS unsigned char* vb, const bf16x8 (&pf)[4], f32x16& ot0, f32x16& ot1) {
; #pragma unroll
;     for (int s = 0; s < 4; ++s) {
;         const s16x4 a00 = __builtin_bit_cast(s16x4, __builtin_amdgcn_ds_read_tr16_b64_v4i16((LAS s16x4*)(vb + (16 * s) * 64)));
;         const s16x4 a01 = __builtin_bit_cast(s16x4, __builtin_amdgcn_ds_read_tr16_b64_v4i16((LAS s16x4*)(vb + (16 * s + 8) * 64)));
;         const s16x4 a10 = __builtin_bit_cast(s16x4, __builtin_amdgcn_ds_read_tr16_b64_v4i16((LAS s16x4*)(vb + 8192 + (16 * s) * 64)));
;         const s16x4 a11 = __builtin_bit_cast(s16x4, __builtin_amdgcn_ds_read_tr16_b64_v4i16((LAS s16x4*)(vb + 8192 + (16 * s + 8) * 64)));
;         const bf16x8 va0 = (bf16x8){a00[0], a00[1], a00[2], a00[3], a01[0], a01[1], a01[2], a01[3]};
;         const bf16x8 va1 = (bf16x8){a10[0], a10[1], a10[2], a10[3], a11[0], a11[1], a11[2], a11[3]};
;         ot0 = __builtin_amdgcn_mfma_f32_32x32x16_bf16(va0, pf[s], ot0, 0, 0, 0); ot1 = __builtin_amdgcn_mfma_f32_32x32x16_bf16(va1, pf[s], ot1, 0, 0, 0); }
; }
; __device__ __forceinline__ void attn2_unit(bf16_t* Z, const bf16_t* Hb, const float* rc, const float* rs, LAS unsigned char* lds, int b, int h, int qblk) {
;     ...
;             a2_exp_pack(sa0, sa1, lsum, pa);
;             a2_pv(vb, pa, ot0, ot1);
;             a2_exp_pack(sb0, sb1, lsum, pb);
;             a2_pv(vb + 64 * 64, pb, ot0, ot1);
;         } else if (2 * kp <= cw) {
;             f32x16 sa0, sa1; bf16x8 pa[4];
;             a2_qk(kb, qf, cneg, sa0, sa1);
;             const float mt = a2_max(sa0, sa1);
;             if (kp == 0 || __builtin_amdgcn_ballot_w64(mt > 8.f) != 0ull) {
;                 const float delta = (kp == 0) ? mt : fmaxf(mt, 0.f), alpha = (kp == 0) ? 0.f : __builtin_amdgcn_exp2f(-delta);
;                 mrun += delta; lsum *= alpha;
; #pragma unroll
;                 for (int r = 0; r < 16; ++r) { ot0[r] *= alpha; ot1[r] *= alpha; sa0[r] -= delta; sa1[r] -= delta; cneg[r] = -mrun; }
;             }
;             a2_exp_pack(sa0, sa1, lsum, pa);
;             a2_pv(vb, pa, ot0, ot1);
;         }
;         __syncthreads();
;     }
	v_mfma_f32_32x32x16_bf16 v[16:31], v[64:67], v[68:71], v[16:31]
	v_add_f32_e64 v64, v220, v110
	v_add_f32_e64 v65, v221, v111
	v_add_f32_e64 v14, v212, v14
	v_add_f32_e64 v15, v213, v15
	v_exp_f32_e32 v216, v87
	v_exp_f32_e32 v116, v76
	v_exp_f32_e32 v118, v77
	v_exp_f32_e32 v98, v78
	v_exp_f32_e32 v96, v79
	s_waitcnt lgkmcnt(2)
	v_mfma_f32_32x32x16_bf16 v[32:47], v[72:75], v[68:71], v[32:47]
	v_add_f32_e64 v14, v14, v64
	v_add_f32_e64 v15, v15, v65
	ds_read_b64_tr_b16 v[64:65], v0 offset:39936
	ds_read_b64_tr_b16 v[66:67], v0 offset:40448
	v_exp_f32_e32 v122, v88
	v_pk_add_f32 v[12:13], v[210:211], v[12:13]
	v_pk_add_f32 v[68:69], v[216:217], v[10:11]
	v_pk_add_f32 v[14:15], v[12:13], v[14:15]
	v_cvt_pk_bf16_f32 v10, v208, v206
	v_cvt_pk_bf16_f32 v11, v204, v120
	v_cvt_pk_bf16_f32 v12, v116, v118
	v_cvt_pk_bf16_f32 v13, v98, v96
	v_pk_add_f32 v[14:15], v[68:69], v[14:15]
	v_pk_add_f32 v[68:69], v[122:123], v[208:209]
	s_waitcnt lgkmcnt(2)
	v_mfma_f32_32x32x16_bf16 v[16:31], v[80:83], v[10:13], v[16:31]
	v_add_f32_e64 v14, v68, v14
	v_add_f32_e64 v15, v69, v15
	ds_read_b64_tr_b16 v[68:69], v0 offset:32768
	ds_read_b64_tr_b16 v[70:71], v0 offset:33280
	v_exp_f32_e32 v126, v89
	v_exp_f32_e32 v104, v90
	v_cvt_pk_bf16_f32 v7, v2, v4
	v_exp_f32_e32 v214, v91
	v_cvt_pk_bf16_f32 v6, v6, v8
	s_waitcnt lgkmcnt(2)
	v_mfma_f32_32x32x16_bf16 v[32:47], v[64:67], v[10:13], v[32:47]
	ds_read_b64_tr_b16 v[2:3], v0 offset:40960
	ds_read_b64_tr_b16 v[4:5], v0 offset:41472
	ds_read_b64_tr_b16 v[10:11], v0 offset:33792
	ds_read_b64_tr_b16 v[12:13], v0 offset:34304
	v_cvt_pk_bf16_f32 v8, v124, v212
	v_cvt_pk_bf16_f32 v9, v210, v216
	v_pk_add_f32 v[72:73], v[126:127], v[206:207]
	v_pk_add_f32 v[64:65], v[104:105], v[204:205]
	v_pk_add_f32 v[14:15], v[72:73], v[14:15]
	v_exp_f32_e32 v106, v92
	s_waitcnt lgkmcnt(4)
	v_mfma_f32_32x32x16_bf16 v[16:31], v[68:71], v[6:9], v[16:31]
	v_add_f32_e64 v14, v64, v14
	v_add_f32_e64 v15, v65, v15
	v_add_f32_e64 v64, v214, v120
	v_add_f32_e64 v65, v215, v121
	v_exp_f32_e32 v108, v93
	v_exp_f32_e32 v102, v94
	v_exp_f32_e32 v100, v95
	v_pk_add_f32 v[14:15], v[64:65], v[14:15]
	ds_read_b64_tr_b16 v[64:65], v0 offset:41984
	ds_read_b64_tr_b16 v[66:67], v0 offset:42496
	s_waitcnt lgkmcnt(4)
	v_mfma_f32_32x32x16_bf16 v[32:47], v[2:5], v[6:9], v[32:47]
	v_add_f32_e64 v2, v106, v116
	v_add_f32_e64 v3, v107, v117
	v_cvt_pk_bf16_f32 v4, v106, v108
	v_add_f32_e64 v6, v2, v14
	v_add_f32_e64 v7, v3, v15
	v_cvt_pk_bf16_f32 v2, v122, v126
	v_cvt_pk_bf16_f32 v3, v104, v214
	v_cvt_pk_bf16_f32 v5, v102, v100
	v_pk_add_f32 v[8:9], v[108:109], v[118:119]
	v_mov_b32_e32 v14, v55
	s_waitcnt lgkmcnt(2)
	v_mfma_f32_32x32x16_bf16 v[16:31], v[10:13], v[2:5], v[16:31]
	v_add_f32_e64 v6, v8, v6
	v_add_f32_e64 v7, v9, v7
	v_add_f32_e64 v8, v102, v98
	v_add_f32_e64 v9, v103, v99
	v_mov_b32_e32 v10, v59
	v_pk_add_f32 v[6:7], v[8:9], v[6:7]
	v_pk_add_f32 v[8:9], v[100:101], v[96:97]
	v_mov_b32_e32 v11, v58
	v_pk_add_f32 v[6:7], v[8:9], v[6:7]
	s_waitcnt lgkmcnt(0)
	v_mfma_f32_32x32x16_bf16 v[32:47], v[64:67], v[2:5], v[32:47]
	v_add_f32_e32 v0, v169, v7
	v_add_f32_e32 v0, v6, v0
	s_add_i32 s47, s47, 1
	s_add_i32 s48, s48, 2
	s_add_i32 s6, s37, s47
	v_lshl_add_u64 v[176:177], v[176:177], 0, v[174:175]
	v_lshl_add_u64 v[178:179], v[178:179], 0, s[18:19]
	v_lshl_add_u64 v[180:181], v[180:181], 0, s[18:19]
	v_lshl_add_u64 v[184:185], v[184:185], 0, v[182:183]
	v_lshl_add_u64 v[188:189], v[188:189], 0, v[186:187]
	s_cmp_lg_u32 s6, 1
	v_lshl_add_u64 v[194:195], v[194:195], 0, v[190:191]
	s_cbranch_scc0 .Lattn_exit_2
	v_mov_b32_e32 v169, v0
	s_bitcmp1_b32 s47, 0
	s_cselect_b32 s6, 0, 0xa800
	s_cmp_ge_u32 s47, s34
	s_waitcnt vmcnt(0) lgkmcnt(0)
	s_barrier
	s_cbranch_scc0 .LBB0_2221
	s_branch .LBB0_2224

; #define LAS __attribute__((address_space(3)))
; __device__ __forceinline__ unsigned cvtpk2(float lo, float hi) { const f32x2 v = {lo, hi}; const bf16x2_n b = __builtin_convertvector(v, bf16x2_n); return __builtin_bit_cast(unsigned, b); }
; __device__ __forceinline__ void a2_exp_pack(f32x16& st0, f32x16& st1, float& lsum, bf16x8 (&pf)[4]) {
;     float ps = 0.f;
; #pragma unroll
;     for (int r = 0; r < 16; ++r) { st0[r] = __builtin_amdgcn_exp2f(st0[r]); st1[r] = __builtin_amdgcn_exp2f(st1[r]); ps += st0[r] + st1[r]; }
;     lsum += ps;
;     u32x4 w;
;     w.x = cvtpk2(st0[0], st0[1]); w.y = cvtpk2(st0[2], st0[3]); w.z = cvtpk2(st0[4], st0[5]); w.w = cvtpk2(st0[6], st0[7]); pf[0] = __builtin_bit_cast(bf16x8, w);
;     w.x = cvtpk2(st0[8], st0[9]); w.y = cvtpk2(st0[10], st0[11]); w.z = cvtpk2(st0[12], st0[13]); w.w = cvtpk2(st0[14], st0[15]); pf[1] = __builtin_bit_cast(bf16x8, w);
;     w.x = cvtpk2(st1[0], st1[1]); w.y = cvtpk2(st1[2], st1[3]); w.z = cvtpk2(st1[4], st1[5]); w.w = cvtpk2(st1[6], st1[7]); pf[2] = __builtin_bit_cast(bf16x8, w);
;     w.x = cvtpk2(st1[8], st1[9]); w.y = cvtpk2(st1[10], st1[11]); w.z = cvtpk2(st1[12], st1[13]); w.w = cvtpk2(st1[14], st1[15]); pf[3] = __builtin_bit_cast(bf16x8, w);
; }
; __device__ __forceinline__ void a2_pv(const LAS unsigned char* vb, const bf16x8 (&pf)[4], f32x16& ot0, f32x16& ot1) {
; #pragma unroll
;     for (int s = 0; s < 4; ++s) {
;         const s16x4 a00 = __builtin_bit_cast(s16x4, __builtin_amdgcn_ds_read_tr16_b64_v4i16((LAS s16x4*)(vb + (16 * s) * 64)));
;         const s16x4 a01 = __builtin_bit_cast(s16x4, __builtin_amdgcn_ds_read_tr16_b64_v4i16((LAS s16x4*)(vb + (16 * s + 8) * 64)));
;         const s16x4 a10 = __builtin_bit_cast(s16x4, __builtin_amdgcn_ds_read_tr16_b64_v4i16((LAS s16x4*)(vb + 8192 + (16 * s) * 64)));
;         const s16x4 a11 = __builtin_bit_cast(s16x4, __builtin_amdgcn_ds_read_tr16_b64_v4i16((LAS s16x4*)(vb + 8192 + (16 * s + 8) * 64)));
;         const bf16x8 va0 = (bf16x8){a00[0], a00[1], a00[2], a00[3], a01[0], a01[1], a01[2], a01[3]};
;         const bf16x8 va1 = (bf16x8){a10[0], a10[1], a10[2], a10[3], a11[0], a11[1], a11[2], a11[3]};
;         ot0 = __builtin_amdgcn_mfma_f32_32x32x16_bf16(va0, pf[s], ot0, 0, 0, 0); ot1 = __builtin_amdgcn_mfma_f32_32x32x16_bf16(va1, pf[s], ot1, 0, 0, 0); }
; }
.LBB0_2289:
	v_add_u32_e32 v0, v2, v218
	v_exp_f32_e32 v195, v112
	v_exp_f32_e32 v7, v96
	v_exp_f32_e32 v113, v113
	v_exp_f32_e32 v9, v97
	v_exp_f32_e32 v199, v114
	v_exp_f32_e32 v3, v98
	v_exp_f32_e32 v115, v115
	v_exp_f32_e32 v5, v99
	v_exp_f32_e32 v201, v116
	v_exp_f32_e32 v15, v117
	v_exp_f32_e32 v13, v118
	v_exp_f32_e32 v11, v119
	s_waitcnt vmcnt(0)
	ds_read_b64_tr_b16 v[96:97], v0 offset:26624
	ds_read_b64_tr_b16 v[98:99], v0 offset:27136
	ds_read_b64_tr_b16 v[212:213], v0 offset:34816
	ds_read_b64_tr_b16 v[214:215], v0 offset:35328
	ds_read_b64_tr_b16 v[220:221], v0 offset:27648
	ds_read_b64_tr_b16 v[222:223], v0 offset:28160
	v_cvt_pk_bf16_f32 v208, v195, v113
	v_cvt_pk_bf16_f32 v209, v199, v115
	v_cvt_pk_bf16_f32 v210, v201, v15
	v_cvt_pk_bf16_f32 v211, v13, v11
	v_exp_f32_e32 v207, v120
	v_exp_f32_e32 v205, v121
	s_waitcnt lgkmcnt(4)
	v_mfma_f32_32x32x16_bf16 v[16:31], v[96:99], v[208:211], v[16:31]
	v_exp_f32_e32 v203, v122
	v_exp_f32_e32 v121, v123
	v_exp_f32_e32 v117, v124
	ds_read_b64_tr_b16 v[224:225], v0 offset:35840
	ds_read_b64_tr_b16 v[226:227], v0 offset:36352
	v_exp_f32_e32 v119, v125
	v_exp_f32_e32 v99, v126
	v_exp_f32_e32 v97, v127
	s_waitcnt lgkmcnt(4)
	v_mfma_f32_32x32x16_bf16 v[32:47], v[212:215], v[208:211], v[32:47]
	v_cvt_pk_bf16_f32 v228, v207, v205
	v_cvt_pk_bf16_f32 v229, v203, v121
	v_cvt_pk_bf16_f32 v230, v117, v119
	v_cvt_pk_bf16_f32 v231, v99, v97
	v_exp_f32_e32 v125, v100
	v_exp_f32_e32 v211, v101
	v_exp_f32_e32 v209, v102
	s_waitcnt lgkmcnt(2)
	v_mfma_f32_32x32x16_bf16 v[16:31], v[220:223], v[228:231], v[16:31]
	v_exp_f32_e32 v215, v103
	ds_read_b64_tr_b16 v[220:221], v0 offset:28672
	ds_read_b64_tr_b16 v[222:223], v0 offset:29184
	v_cvt_pk_bf16_f32 v100, v7, v9
	v_cvt_pk_bf16_f32 v101, v3, v5
	v_cvt_pk_bf16_f32 v102, v125, v211
	v_cvt_pk_bf16_f32 v103, v209, v215
	v_exp_f32_e32 v123, v104
	s_waitcnt lgkmcnt(2)
	v_mfma_f32_32x32x16_bf16 v[32:47], v[224:227], v[228:231], v[32:47]
	ds_read_b64_tr_b16 v[224:225], v0 offset:36864
	ds_read_b64_tr_b16 v[226:227], v0 offset:37376
	ds_read_b64_tr_b16 v[228:229], v0 offset:29696
	ds_read_b64_tr_b16 v[230:231], v0 offset:30208
	v_exp_f32_e32 v127, v105
	v_exp_f32_e32 v105, v106
	v_exp_f32_e32 v213, v107
	v_exp_f32_e32 v107, v108
	v_exp_f32_e32 v109, v109
	v_exp_f32_e32 v194, v64
	s_waitcnt lgkmcnt(4)
	v_mfma_f32_32x32x16_bf16 v[16:31], v[220:223], v[100:103], v[16:31]
	ds_read_b64_tr_b16 v[220:221], v0 offset:37888
	ds_read_b64_tr_b16 v[222:223], v0 offset:38400
	v_exp_f32_e32 v6, v80
	v_exp_f32_e32 v112, v65
	v_exp_f32_e32 v8, v81
	v_exp_f32_e32 v198, v66
	v_exp_f32_e32 v2, v82
	v_exp_f32_e32 v114, v67
	s_waitcnt lgkmcnt(4)
	v_mfma_f32_32x32x16_bf16 v[32:47], v[224:227], v[100:103], v[32:47]
	v_exp_f32_e32 v103, v110
	v_exp_f32_e32 v101, v111
	v_exp_f32_e32 v4, v83
	v_cvt_pk_bf16_f32 v224, v123, v127
	v_cvt_pk_bf16_f32 v225, v105, v213
	v_cvt_pk_bf16_f32 v226, v107, v109
	v_cvt_pk_bf16_f32 v227, v103, v101
	v_pk_add_f32 v[64:65], v[6:7], v[194:195]
	v_pk_add_f32 v[66:67], v[8:9], v[112:113]
	s_waitcnt lgkmcnt(2)
	v_mfma_f32_32x32x16_bf16 v[16:31], v[228:231], v[224:227], v[16:31]
	v_add_f32_e64 v64, v64, 0
	v_add_f32_e64 v65, v65, 0
	v_exp_f32_e32 v200, v68
	v_pk_add_f32 v[64:65], v[66:67], v[64:65]
	v_pk_add_f32 v[66:67], v[2:3], v[198:199]
	v_exp_f32_e32 v14, v69
	v_pk_add_f32 v[64:65], v[66:67], v[64:65]
	v_pk_add_f32 v[66:67], v[4:5], v[114:115]
	s_waitcnt lgkmcnt(0)
	v_mfma_f32_32x32x16_bf16 v[32:47], v[220:223], v[224:227], v[32:47]
	v_add_f32_e64 v110, v66, v64
	v_add_f32_e64 v111, v67, v65
	v_exp_f32_e32 v12, v70
	v_exp_f32_e32 v10, v71
	ds_read_b64_tr_b16 v[64:65], v0 offset:30720
	ds_read_b64_tr_b16 v[66:67], v0 offset:31232
	v_exp_f32_e32 v124, v84
	v_exp_f32_e32 v206, v72
	v_exp_f32_e32 v204, v73
	v_exp_f32_e32 v202, v74
	v_exp_f32_e32 v120, v75
	ds_read_b64_tr_b16 v[72:73], v0 offset:38912
	ds_read_b64_tr_b16 v[74:75], v0 offset:39424
	ds_read_b64_tr_b16 v[80:81], v0 offset:31744
	ds_read_b64_tr_b16 v[82:83], v0 offset:32256
	v_exp_f32_e32 v210, v85
	v_cvt_pk_bf16_f32 v68, v194, v112
	v_cvt_pk_bf16_f32 v69, v198, v114
	v_cvt_pk_bf16_f32 v70, v200, v14
	v_cvt_pk_bf16_f32 v71, v12, v10
	v_pk_add_f32 v[216:217], v[124:125], v[200:201]
	v_exp_f32_e32 v208, v86
	s_waitcnt lgkmcnt(4)
	v_mfma_f32_32x32x16_bf16 v[16:31], v[64:67], v[68:71], v[16:31]
	v_add_f32_e64 v64, v216, v110
	v_add_f32_e64 v65, v217, v111
	v_add_f32_e64 v14, v210, v14
	v_add_f32_e64 v15, v211, v15
	v_exp_f32_e32 v214, v87
	v_exp_f32_e32 v116, v76
	v_exp_f32_e32 v118, v77
	v_exp_f32_e32 v98, v78
	v_exp_f32_e32 v96, v79
	s_waitcnt lgkmcnt(2)
; #define LAS __attribute__((address_space(3)))
; __device__ __forceinline__ void a2_pv(const LAS unsigned char* vb, const bf16x8 (&pf)[4], f32x16& ot0, f32x16& ot1) {
; #pragma unroll
;     for (int s = 0; s < 4; ++s) {
;         const s16x4 a00 = __builtin_bit_cast(s16x4, __builtin_amdgcn_ds_read_tr16_b64_v4i16((LAS s16x4*)(vb + (16 * s) * 64)));
;         const s16x4 a01 = __builtin_bit_cast(s16x4, __builtin_amdgcn_ds_read_tr16_b64_v4i16((LAS s16x4*)(vb + (16 * s + 8) * 64)));
;         const s16x4 a10 = __builtin_bit_cast(s16x4, __builtin_amdgcn_ds_read_tr16_b64_v4i16((LAS s16x4*)(vb + 8192 + (16 * s) * 64)));
;         const s16x4 a11 = __builtin_bit_cast(s16x4, __builtin_amdgcn_ds_read_tr16_b64_v4i16((LAS s16x4*)(vb + 8192 + (16 * s + 8) * 64)));
;         const bf16x8 va0 = (bf16x8){a00[0], a00[1], a00[2], a00[3], a01[0], a01[1], a01[2], a01[3]};
;         const bf16x8 va1 = (bf16x8){a10[0], a10[1], a10[2], a10[3], a11[0], a11[1], a11[2], a11[3]};
;         ot0 = __builtin_amdgcn_mfma_f32_32x32x16_bf16(va0, pf[s], ot0, 0, 0, 0); ot1 = __builtin_amdgcn_mfma_f32_32x32x16_bf16(va1, pf[s], ot1, 0, 0, 0); }
; }
; __device__ __forceinline__ void attn2_unit(bf16_t* Z, const bf16_t* Hb, const float* rc, const float* rs, LAS unsigned char* lds, int b, int h, int qblk) {
;     ...
;             a2_exp_pack(sa0, sa1, lsum, pa);
;             a2_pv(vb, pa, ot0, ot1);
;             a2_exp_pack(sb0, sb1, lsum, pb);
;             a2_pv(vb + 64 * 64, pb, ot0, ot1);
;         } else if (2 * kp <= cw) {
;             f32x16 sa0, sa1; bf16x8 pa[4];
;             a2_qk(kb, qf, cneg, sa0, sa1);
;             const float mt = a2_max(sa0, sa1);
;             if (kp == 0 || __builtin_amdgcn_ballot_w64(mt > 8.f) != 0ull) {
;                 const float delta = (kp == 0) ? mt : fmaxf(mt, 0.f), alpha = (kp == 0) ? 0.f : __builtin_amdgcn_exp2f(-delta);
;                 mrun += delta; lsum *= alpha;
; #pragma unroll
;                 for (int r = 0; r < 16; ++r) { ot0[r] *= alpha; ot1[r] *= alpha; sa0[r] -= delta; sa1[r] -= delta; cneg[r] = -mrun; }
;             }
;             a2_exp_pack(sa0, sa1, lsum, pa);
;             a2_pv(vb, pa, ot0, ot1);
;         }
;         __syncthreads();
;     }
	v_mfma_f32_32x32x16_bf16 v[32:47], v[72:75], v[68:71], v[32:47]
	v_add_f32_e64 v14, v14, v64
	v_add_f32_e64 v15, v15, v65
	ds_read_b64_tr_b16 v[64:65], v0 offset:39936
	ds_read_b64_tr_b16 v[66:67], v0 offset:40448
	v_exp_f32_e32 v122, v88
	v_pk_add_f32 v[12:13], v[208:209], v[12:13]
	v_pk_add_f32 v[68:69], v[214:215], v[10:11]
	v_pk_add_f32 v[14:15], v[12:13], v[14:15]
	v_cvt_pk_bf16_f32 v10, v206, v204
	v_cvt_pk_bf16_f32 v11, v202, v120
	v_cvt_pk_bf16_f32 v12, v116, v118
	v_cvt_pk_bf16_f32 v13, v98, v96
	v_pk_add_f32 v[14:15], v[68:69], v[14:15]
	v_pk_add_f32 v[68:69], v[122:123], v[206:207]
	s_waitcnt lgkmcnt(2)
	v_mfma_f32_32x32x16_bf16 v[16:31], v[80:83], v[10:13], v[16:31]
	v_add_f32_e64 v14, v68, v14
	v_add_f32_e64 v15, v69, v15
	ds_read_b64_tr_b16 v[68:69], v0 offset:32768
	ds_read_b64_tr_b16 v[70:71], v0 offset:33280
	v_exp_f32_e32 v126, v89
	v_exp_f32_e32 v104, v90
	v_cvt_pk_bf16_f32 v7, v2, v4
	v_exp_f32_e32 v212, v91
	v_cvt_pk_bf16_f32 v6, v6, v8
	s_waitcnt lgkmcnt(2)
	v_mfma_f32_32x32x16_bf16 v[32:47], v[64:67], v[10:13], v[32:47]
	ds_read_b64_tr_b16 v[2:3], v0 offset:40960
	ds_read_b64_tr_b16 v[4:5], v0 offset:41472
	ds_read_b64_tr_b16 v[10:11], v0 offset:33792
	ds_read_b64_tr_b16 v[12:13], v0 offset:34304
	v_cvt_pk_bf16_f32 v8, v124, v210
	v_cvt_pk_bf16_f32 v9, v208, v214
	v_pk_add_f32 v[72:73], v[126:127], v[204:205]
	v_pk_add_f32 v[64:65], v[104:105], v[202:203]
	v_pk_add_f32 v[14:15], v[72:73], v[14:15]
	v_exp_f32_e32 v106, v92
	s_waitcnt lgkmcnt(4)
	v_mfma_f32_32x32x16_bf16 v[16:31], v[68:71], v[6:9], v[16:31]
	v_add_f32_e64 v14, v64, v14
	v_add_f32_e64 v15, v65, v15
	v_add_f32_e64 v64, v212, v120
	v_add_f32_e64 v65, v213, v121
	v_exp_f32_e32 v108, v93
	v_exp_f32_e32 v102, v94
	v_exp_f32_e32 v100, v95
	v_pk_add_f32 v[14:15], v[64:65], v[14:15]
	ds_read_b64_tr_b16 v[64:65], v0 offset:41984
	ds_read_b64_tr_b16 v[66:67], v0 offset:42496
	s_waitcnt lgkmcnt(4)
	v_mfma_f32_32x32x16_bf16 v[32:47], v[2:5], v[6:9], v[32:47]
	v_add_f32_e64 v2, v106, v116
	v_add_f32_e64 v3, v107, v117
	v_cvt_pk_bf16_f32 v4, v106, v108
	v_add_f32_e64 v6, v2, v14
	v_add_f32_e64 v7, v3, v15
	v_cvt_pk_bf16_f32 v2, v122, v126
	v_cvt_pk_bf16_f32 v3, v104, v212
	v_cvt_pk_bf16_f32 v5, v102, v100
	v_pk_add_f32 v[8:9], v[108:109], v[118:119]
	v_mov_b32_e32 v14, v55
	s_waitcnt lgkmcnt(2)
	v_mfma_f32_32x32x16_bf16 v[16:31], v[10:13], v[2:5], v[16:31]
	v_add_f32_e64 v6, v8, v6
	v_add_f32_e64 v7, v9, v7
	v_add_f32_e64 v8, v102, v98
	v_add_f32_e64 v9, v103, v99
	v_mov_b32_e32 v10, v59
	v_pk_add_f32 v[6:7], v[8:9], v[6:7]
	v_pk_add_f32 v[8:9], v[100:101], v[96:97]
	v_mov_b32_e32 v11, v58
	v_pk_add_f32 v[6:7], v[8:9], v[6:7]
	s_waitcnt lgkmcnt(0)
	v_mfma_f32_32x32x16_bf16 v[32:47], v[64:67], v[2:5], v[32:47]
	v_add_f32_e32 v0, v169, v7
	v_add_f32_e32 v0, v6, v0
	s_add_i32 s31, s31, 1
	s_add_i32 s42, s42, 2
	s_add_i32 s6, s38, s31
	v_lshl_add_u64 v[174:175], v[174:175], 0, v[170:171]
	v_lshl_add_u64 v[176:177], v[176:177], 0, s[18:19]
	v_lshl_add_u64 v[178:179], v[178:179], 0, s[18:19]
	v_lshl_add_u64 v[182:183], v[182:183], 0, v[180:181]
	v_lshl_add_u64 v[186:187], v[186:187], 0, v[184:185]
	s_cmp_lg_u32 s6, 1
	v_lshl_add_u64 v[190:191], v[190:191], 0, v[188:189]
	s_cbranch_scc0 .Lattn_exit_3
	v_mov_b32_e32 v169, v0
	s_bitcmp1_b32 s31, 0
	s_cselect_b32 s6, 0, 0xa800
	s_cmp_ge_u32 s31, s36
	s_waitcnt vmcnt(0) lgkmcnt(0)
	s_barrier
	s_cbranch_scc0 .LBB0_2267
	s_branch .LBB0_2270
.Lattn_exit_3:
	s_waitcnt vmcnt(0) lgkmcnt(0)
	s_barrier
	s_nop 7
	s_nop 7
	v_mov_b64_e32 v[110:111], v[30:31]
	v_mov_b32_e32 v6, v63
	v_mov_b32_e32 v7, v62
	v_mov_b32_e32 v8, v61
	v_mov_b32_e32 v9, v60
	v_mov_b64_e32 v[126:127], v[46:47]
	v_mov_b32_e32 v12, v57
	v_mov_b32_e32 v13, v56
	v_mov_b32_e32 v15, v54
	v_mov_b32_e32 v194, v53
	v_mov_b32_e32 v195, v52
	v_mov_b32_e32 v198, v51
	v_mov_b32_e32 v199, v50
	v_mov_b32_e32 v200, v49
	v_mov_b32_e32 v4, v48
	v_mov_b32_e32 v5, v165
	v_mov_b64_e32 v[108:109], v[28:29]
	v_mov_b64_e32 v[106:107], v[26:27]
	v_mov_b64_e32 v[104:105], v[24:25]
	v_mov_b64_e32 v[102:103], v[22:23]
	v_mov_b64_e32 v[100:101], v[20:21]
	v_mov_b64_e32 v[98:99], v[18:19]
	v_mov_b64_e32 v[96:97], v[16:17]
	v_mov_b64_e32 v[124:125], v[44:45]
	v_mov_b64_e32 v[122:123], v[42:43]
	v_mov_b64_e32 v[120:121], v[40:41]
	v_mov_b64_e32 v[118:119], v[38:39]
	v_mov_b64_e32 v[116:117], v[36:37]
	v_mov_b64_e32 v[114:115], v[34:35]
	v_mov_b64_e32 v[112:113], v[32:33]
	s_branch .LBB0_2201
